# P11 PLE-gate epilogue: hoist the 8 row-sumsq loads ahead of the epilogue with counted vmcnt waits
# speedup vs baseline: 1.0048x; 1.0015x over previous
.LBB0_167:
	s_add_u32 s72, s60, 0xfffc0080
	s_addc_u32 s73, s61, -1
	s_add_i32 s76, 16, 0x10000
	s_cmp_eq_u32 vcc_lo, 12
	s_cselect_b32 s75, s15, s73
	s_cselect_b32 s74, s78, s72
	v_add_u32_e32 v150, s76, v80
	s_cselect_b32 s73, s11, s97
	s_cselect_b32 s72, s79, s96
	s_add_i32 vcc_hi, 16, 0x14000
	ds_read_b128 v[142:145], v150
	ds_read_b128 v[146:149], v150 offset:1024
	ds_read_b128 v[160:163], v150 offset:2048
	ds_read_b128 v[166:169], v150 offset:3072
	v_add_u32_e32 v150, vcc_hi, v80
	ds_read_b128 v[170:173], v150
	ds_read_b128 v[174:177], v150 offset:1024
	ds_read_b128 v[178:181], v150 offset:2048
	ds_read_b128 v[182:185], v150 offset:3072
	v_lshl_add_u64 v[150:151], s[60:61], 0, v[138:139]
	s_add_i32 m0, s13, 0xc000
	ds_read_b128 v[186:189], v164
	ds_read_b128 v[204:207], v164 offset:1024
	ds_read_b128 v[214:217], v164 offset:2048
	ds_read_b128 v[218:221], v164 offset:3072
	ds_read_b128 v[222:225], v164 offset:4096
	ds_read_b128 v[226:229], v164 offset:5120
	ds_read_b128 v[230:233], v164 offset:6144
	ds_read_b128 v[234:237], v164 offset:7168
	global_load_lds_dwordx4 v[150:151], off
	v_lshl_add_u64 v[150:151], s[60:61], 0, v[140:141]
	s_add_i32 m0, s13, 0xe000
	s_nop 0
	global_load_lds_dwordx4 v[150:151], off
	s_waitcnt vmcnt(8)
	s_waitcnt lgkmcnt(0)
	s_barrier
	s_waitcnt lgkmcnt(0)
	v_mfma_f32_16x16x32_bf16 v[126:129], v[142:145], v[186:189], v[126:129]
	v_mfma_f32_16x16x32_bf16 v[122:125], v[160:163], v[186:189], v[122:125]
	v_mfma_f32_16x16x32_bf16 v[110:113], v[142:145], v[214:217], v[110:113]
	v_mfma_f32_16x16x32_bf16 v[106:109], v[160:163], v[214:217], v[106:109]
	v_mfma_f32_16x16x32_bf16 v[94:97], v[142:145], v[222:225], v[94:97]
	v_mfma_f32_16x16x32_bf16 v[90:93], v[160:163], v[222:225], v[90:93]
	v_mfma_f32_16x16x32_bf16 v[76:79], v[142:145], v[230:233], v[76:79]
	v_mfma_f32_16x16x32_bf16 v[72:75], v[160:163], v[230:233], v[72:75]
	v_mfma_f32_16x16x32_bf16 v[126:129], v[146:149], v[204:207], v[126:129]
	v_mfma_f32_16x16x32_bf16 v[122:125], v[166:169], v[204:207], v[122:125]
	v_mfma_f32_16x16x32_bf16 v[110:113], v[146:149], v[218:221], v[110:113]
	v_mfma_f32_16x16x32_bf16 v[106:109], v[166:169], v[218:221], v[106:109]
	v_mfma_f32_16x16x32_bf16 v[94:97], v[146:149], v[226:229], v[94:97]
	v_mfma_f32_16x16x32_bf16 v[90:93], v[166:169], v[226:229], v[90:93]
	v_mfma_f32_16x16x32_bf16 v[76:79], v[146:149], v[234:237], v[76:79]
	v_mfma_f32_16x16x32_bf16 v[72:75], v[166:169], v[234:237], v[72:75]
	v_mfma_f32_16x16x32_bf16 v[118:121], v[170:173], v[186:189], v[118:121]
	v_mfma_f32_16x16x32_bf16 v[114:117], v[178:181], v[186:189], v[114:117]
	v_mfma_f32_16x16x32_bf16 v[102:105], v[170:173], v[214:217], v[102:105]
	v_mfma_f32_16x16x32_bf16 v[98:101], v[178:181], v[214:217], v[98:101]
	v_mfma_f32_16x16x32_bf16 v[86:89], v[170:173], v[222:225], v[86:89]
	v_mfma_f32_16x16x32_bf16 v[82:85], v[178:181], v[222:225], v[82:85]
	v_mfma_f32_16x16x32_bf16 v[68:71], v[170:173], v[230:233], v[68:71]
	v_mfma_f32_16x16x32_bf16 v[64:67], v[178:181], v[230:233], v[64:67]
	v_mfma_f32_16x16x32_bf16 v[118:121], v[174:177], v[204:207], v[118:121]
	v_mfma_f32_16x16x32_bf16 v[114:117], v[182:185], v[204:207], v[114:117]
	v_mfma_f32_16x16x32_bf16 v[102:105], v[174:177], v[218:221], v[102:105]
	v_mfma_f32_16x16x32_bf16 v[98:101], v[182:185], v[218:221], v[98:101]
	v_mfma_f32_16x16x32_bf16 v[86:89], v[174:177], v[226:229], v[86:89]
	v_mfma_f32_16x16x32_bf16 v[82:85], v[182:185], v[226:229], v[82:85]
	v_mfma_f32_16x16x32_bf16 v[68:71], v[174:177], v[234:237], v[68:71]
	v_mfma_f32_16x16x32_bf16 v[64:67], v[182:185], v[234:237], v[64:67]
	s_barrier
	s_add_i32 s76, s76, s4
	v_lshl_add_u64 v[150:151], s[72:73], 0, v[134:135]
	s_mov_b32 m0, s76
	ds_read_b128 v[186:189], v164 offset:16384
	ds_read_b128 v[204:207], v164 offset:17408
	ds_read_b128 v[214:217], v164 offset:18432
	ds_read_b128 v[218:221], v164 offset:19456
	ds_read_b128 v[222:225], v164 offset:20480
	ds_read_b128 v[226:229], v164 offset:21504
	ds_read_b128 v[230:233], v164 offset:22528
	ds_read_b128 v[234:237], v164 offset:23552
	global_load_lds_dwordx4 v[150:151], off
	s_add_i32 m0, s76, 0x2000
	s_add_u32 s76, s72, 0x40000
	v_lshl_add_u64 v[190:191], s[72:73], 0, v[130:131]
	s_addc_u32 s77, s73, 0
	s_add_i32 vcc_hi, vcc_hi, s4
	global_load_lds_dwordx4 v[190:191], off
	v_lshl_add_u64 v[208:209], s[76:77], 0, v[134:135]
	s_mov_b32 m0, vcc_hi
	v_lshl_add_u64 v[238:239], s[74:75], 0, v[132:133]
	global_load_lds_dwordx4 v[208:209], off
	v_lshl_add_u64 v[208:209], s[76:77], 0, v[130:131]
	s_add_i32 m0, vcc_hi, 0x2000
	s_nop 0
	global_load_lds_dwordx4 v[208:209], off
	v_lshl_add_u64 v[208:209], s[74:75], 0, v[136:137]
	s_mov_b32 m0, s13
	s_nop 0
	global_load_lds_dwordx4 v[208:209], off
	s_mov_b32 m0, s25
	s_nop 0
	global_load_lds_dwordx4 v[238:239], off
	s_waitcnt vmcnt(8)
	s_waitcnt lgkmcnt(0)
	s_barrier
	s_waitcnt lgkmcnt(0)
	v_mfma_f32_16x16x32_bf16 v[60:63], v[142:145], v[186:189], v[60:63]
	v_mfma_f32_16x16x32_bf16 v[56:59], v[160:163], v[186:189], v[56:59]
	v_mfma_f32_16x16x32_bf16 v[44:47], v[142:145], v[214:217], v[44:47]
	v_mfma_f32_16x16x32_bf16 v[40:43], v[160:163], v[214:217], v[40:43]
	v_mfma_f32_16x16x32_bf16 v[28:31], v[142:145], v[222:225], v[28:31]
	v_mfma_f32_16x16x32_bf16 v[24:27], v[160:163], v[222:225], v[24:27]
	v_mfma_f32_16x16x32_bf16 v[12:15], v[142:145], v[230:233], v[12:15]
	v_mfma_f32_16x16x32_bf16 v[8:11], v[160:163], v[230:233], v[8:11]
	v_mfma_f32_16x16x32_bf16 v[60:63], v[146:149], v[204:207], v[60:63]
	v_mfma_f32_16x16x32_bf16 v[56:59], v[166:169], v[204:207], v[56:59]
	v_mfma_f32_16x16x32_bf16 v[44:47], v[146:149], v[218:221], v[44:47]
	v_mfma_f32_16x16x32_bf16 v[40:43], v[166:169], v[218:221], v[40:43]
	v_mfma_f32_16x16x32_bf16 v[28:31], v[146:149], v[226:229], v[28:31]
	v_mfma_f32_16x16x32_bf16 v[24:27], v[166:169], v[226:229], v[24:27]
	v_mfma_f32_16x16x32_bf16 v[12:15], v[146:149], v[234:237], v[12:15]
	v_mfma_f32_16x16x32_bf16 v[8:11], v[166:169], v[234:237], v[8:11]
	v_mfma_f32_16x16x32_bf16 v[52:55], v[170:173], v[186:189], v[52:55]
	v_mfma_f32_16x16x32_bf16 v[48:51], v[178:181], v[186:189], v[48:51]
	v_mfma_f32_16x16x32_bf16 v[36:39], v[170:173], v[214:217], v[36:39]
	v_mfma_f32_16x16x32_bf16 v[32:35], v[178:181], v[214:217], v[32:35]
	v_mfma_f32_16x16x32_bf16 v[20:23], v[170:173], v[222:225], v[20:23]
	v_mfma_f32_16x16x32_bf16 v[16:19], v[178:181], v[222:225], v[16:19]
	v_mfma_f32_16x16x32_bf16 v[4:7], v[170:173], v[230:233], v[4:7]
	v_mfma_f32_16x16x32_bf16 v[0:3], v[178:181], v[230:233], v[0:3]
	v_mfma_f32_16x16x32_bf16 v[52:55], v[174:177], v[204:207], v[52:55]
	v_mfma_f32_16x16x32_bf16 v[48:51], v[182:185], v[204:207], v[48:51]
	v_mfma_f32_16x16x32_bf16 v[36:39], v[174:177], v[218:221], v[36:39]
	v_mfma_f32_16x16x32_bf16 v[32:35], v[182:185], v[218:221], v[32:35]
	v_mfma_f32_16x16x32_bf16 v[20:23], v[174:177], v[226:229], v[20:23]
	v_mfma_f32_16x16x32_bf16 v[16:19], v[182:185], v[226:229], v[16:19]
	v_mfma_f32_16x16x32_bf16 v[4:7], v[174:177], v[234:237], v[4:7]
	v_mfma_f32_16x16x32_bf16 v[0:3], v[182:185], v[234:237], v[0:3]
	s_barrier
	s_add_i32 s76, 16, 0x18000
	v_add_u32_e32 v165, s76, v80
	s_add_i32 s77, 16, 0x1c000
	ds_read_b128 v[142:145], v165
	ds_read_b128 v[146:149], v165 offset:1024
	ds_read_b128 v[160:163], v165 offset:2048
	ds_read_b128 v[166:169], v165 offset:3072
	v_add_u32_e32 v165, s77, v80
	ds_read_b128 v[170:173], v165
	ds_read_b128 v[174:177], v165 offset:1024
	ds_read_b128 v[178:181], v165 offset:2048
	ds_read_b128 v[182:185], v165 offset:3072
	s_add_u32 s74, s74, 0x40000
	s_addc_u32 s75, s75, 0
	s_mov_b32 m0, s30
	v_lshl_add_u64 v[240:241], s[74:75], 0, v[136:137]
	ds_read_b128 v[186:189], v164 offset:32768
	ds_read_b128 v[204:207], v164 offset:33792
	ds_read_b128 v[214:217], v164 offset:34816
	ds_read_b128 v[218:221], v164 offset:35840
	ds_read_b128 v[222:225], v164 offset:36864
	ds_read_b128 v[226:229], v164 offset:37888
	ds_read_b128 v[230:233], v164 offset:38912
	ds_read_b128 v[234:237], v164 offset:39936
	global_load_lds_dwordx4 v[240:241], off
	v_lshl_add_u64 v[240:241], s[74:75], 0, v[132:133]
	s_mov_b32 m0, s33
	s_nop 0
	global_load_lds_dwordx4 v[240:241], off
	s_waitcnt vmcnt(8)
	s_waitcnt lgkmcnt(0)
	s_barrier
	s_waitcnt lgkmcnt(0)
	v_mfma_f32_16x16x32_bf16 v[126:129], v[142:145], v[186:189], v[126:129]
	v_mfma_f32_16x16x32_bf16 v[122:125], v[160:163], v[186:189], v[122:125]
	v_mfma_f32_16x16x32_bf16 v[110:113], v[142:145], v[214:217], v[110:113]
	v_mfma_f32_16x16x32_bf16 v[106:109], v[160:163], v[214:217], v[106:109]
	v_mfma_f32_16x16x32_bf16 v[94:97], v[142:145], v[222:225], v[94:97]
	v_mfma_f32_16x16x32_bf16 v[90:93], v[160:163], v[222:225], v[90:93]
	v_mfma_f32_16x16x32_bf16 v[76:79], v[142:145], v[230:233], v[76:79]
	v_mfma_f32_16x16x32_bf16 v[72:75], v[160:163], v[230:233], v[72:75]
	v_mfma_f32_16x16x32_bf16 v[126:129], v[146:149], v[204:207], v[126:129]
	v_mfma_f32_16x16x32_bf16 v[122:125], v[166:169], v[204:207], v[122:125]
	v_mfma_f32_16x16x32_bf16 v[110:113], v[146:149], v[218:221], v[110:113]
	v_mfma_f32_16x16x32_bf16 v[106:109], v[166:169], v[218:221], v[106:109]
	v_mfma_f32_16x16x32_bf16 v[94:97], v[146:149], v[226:229], v[94:97]
	v_mfma_f32_16x16x32_bf16 v[90:93], v[166:169], v[226:229], v[90:93]
	v_mfma_f32_16x16x32_bf16 v[76:79], v[146:149], v[234:237], v[76:79]
	v_mfma_f32_16x16x32_bf16 v[72:75], v[166:169], v[234:237], v[72:75]
	v_mfma_f32_16x16x32_bf16 v[118:121], v[170:173], v[186:189], v[118:121]
	v_mfma_f32_16x16x32_bf16 v[114:117], v[178:181], v[186:189], v[114:117]
	v_mfma_f32_16x16x32_bf16 v[102:105], v[170:173], v[214:217], v[102:105]
	v_mfma_f32_16x16x32_bf16 v[98:101], v[178:181], v[214:217], v[98:101]
	v_mfma_f32_16x16x32_bf16 v[86:89], v[170:173], v[222:225], v[86:89]
	v_mfma_f32_16x16x32_bf16 v[82:85], v[178:181], v[222:225], v[82:85]
	v_mfma_f32_16x16x32_bf16 v[68:71], v[170:173], v[230:233], v[68:71]
	v_mfma_f32_16x16x32_bf16 v[64:67], v[178:181], v[230:233], v[64:67]
	v_mfma_f32_16x16x32_bf16 v[118:121], v[174:177], v[204:207], v[118:121]
	v_mfma_f32_16x16x32_bf16 v[114:117], v[182:185], v[204:207], v[114:117]
	v_mfma_f32_16x16x32_bf16 v[102:105], v[174:177], v[218:221], v[102:105]
	v_mfma_f32_16x16x32_bf16 v[98:101], v[182:185], v[218:221], v[98:101]
	v_mfma_f32_16x16x32_bf16 v[86:89], v[174:177], v[226:229], v[86:89]
	v_mfma_f32_16x16x32_bf16 v[82:85], v[182:185], v[226:229], v[82:85]
	v_mfma_f32_16x16x32_bf16 v[68:71], v[174:177], v[234:237], v[68:71]
	v_mfma_f32_16x16x32_bf16 v[64:67], v[182:185], v[234:237], v[64:67]
	s_barrier
	s_add_i32 s74, s76, s4
	v_lshl_add_u64 v[150:151], v[150:151], 0, s[20:21]
	s_mov_b32 m0, s74
	ds_read_b128 v[186:189], v164 offset:49152
	ds_read_b128 v[204:207], v164 offset:50176
	ds_read_b128 v[214:217], v164 offset:51200
	ds_read_b128 v[218:221], v164 offset:52224
	ds_read_b128 v[222:225], v164 offset:53248
	ds_read_b128 v[226:229], v164 offset:54272
	ds_read_b128 v[230:233], v164 offset:55296
	ds_read_b128 v[234:237], v164 offset:56320
	global_load_lds_dwordx4 v[150:151], off
	s_add_i32 m0, s74, 0x2000
	s_add_u32 s72, s72, 0x40080
	v_lshl_add_u64 v[150:151], v[190:191], 0, s[20:21]
	s_addc_u32 s73, s73, 0
	s_add_i32 s74, s77, s4
	global_load_lds_dwordx4 v[150:151], off
	v_lshl_add_u64 v[150:151], s[72:73], 0, v[134:135]
	s_mov_b32 m0, s74
	s_nop 0
	global_load_lds_dwordx4 v[150:151], off
	v_lshl_add_u64 v[150:151], s[72:73], 0, v[130:131]
	s_add_i32 m0, s74, 0x2000
	s_nop 0
	global_load_lds_dwordx4 v[150:151], off
	v_lshl_add_u64 v[150:151], v[208:209], 0, s[20:21]
	s_mov_b32 m0, s34
	s_nop 0
	global_load_lds_dwordx4 v[150:151], off
	v_lshl_add_u64 v[150:151], v[238:239], 0, s[20:21]
	s_mov_b32 m0, s36
	s_nop 0
	global_load_lds_dwordx4 v[150:151], off
	s_waitcnt vmcnt(8)
	s_waitcnt lgkmcnt(0)
	s_barrier
	s_waitcnt lgkmcnt(0)
	v_mfma_f32_16x16x32_bf16 v[60:63], v[142:145], v[186:189], v[60:63]
	v_mfma_f32_16x16x32_bf16 v[56:59], v[160:163], v[186:189], v[56:59]
	v_mfma_f32_16x16x32_bf16 v[44:47], v[142:145], v[214:217], v[44:47]
	v_mfma_f32_16x16x32_bf16 v[40:43], v[160:163], v[214:217], v[40:43]
	v_mfma_f32_16x16x32_bf16 v[28:31], v[142:145], v[222:225], v[28:31]
	v_mfma_f32_16x16x32_bf16 v[24:27], v[160:163], v[222:225], v[24:27]
	v_mfma_f32_16x16x32_bf16 v[12:15], v[142:145], v[230:233], v[12:15]
	v_mfma_f32_16x16x32_bf16 v[8:11], v[160:163], v[230:233], v[8:11]
	v_mfma_f32_16x16x32_bf16 v[60:63], v[146:149], v[204:207], v[60:63]
	v_mfma_f32_16x16x32_bf16 v[56:59], v[166:169], v[204:207], v[56:59]
	v_mfma_f32_16x16x32_bf16 v[44:47], v[146:149], v[218:221], v[44:47]
	v_mfma_f32_16x16x32_bf16 v[40:43], v[166:169], v[218:221], v[40:43]
	v_mfma_f32_16x16x32_bf16 v[28:31], v[146:149], v[226:229], v[28:31]
	v_mfma_f32_16x16x32_bf16 v[24:27], v[166:169], v[226:229], v[24:27]
	v_mfma_f32_16x16x32_bf16 v[12:15], v[146:149], v[234:237], v[12:15]
	v_mfma_f32_16x16x32_bf16 v[8:11], v[166:169], v[234:237], v[8:11]
	v_mfma_f32_16x16x32_bf16 v[52:55], v[170:173], v[186:189], v[52:55]
	v_mfma_f32_16x16x32_bf16 v[48:51], v[178:181], v[186:189], v[48:51]
	v_mfma_f32_16x16x32_bf16 v[36:39], v[170:173], v[214:217], v[36:39]
	v_mfma_f32_16x16x32_bf16 v[32:35], v[178:181], v[214:217], v[32:35]
	v_mfma_f32_16x16x32_bf16 v[20:23], v[170:173], v[222:225], v[20:23]
	v_mfma_f32_16x16x32_bf16 v[16:19], v[178:181], v[222:225], v[16:19]
	v_mfma_f32_16x16x32_bf16 v[4:7], v[170:173], v[230:233], v[4:7]
	v_mfma_f32_16x16x32_bf16 v[0:3], v[178:181], v[230:233], v[0:3]
	v_mfma_f32_16x16x32_bf16 v[52:55], v[174:177], v[204:207], v[52:55]
	v_mfma_f32_16x16x32_bf16 v[48:51], v[182:185], v[204:207], v[48:51]
	v_mfma_f32_16x16x32_bf16 v[36:39], v[174:177], v[218:221], v[36:39]
	v_mfma_f32_16x16x32_bf16 v[32:35], v[182:185], v[218:221], v[32:35]
	v_mfma_f32_16x16x32_bf16 v[20:23], v[174:177], v[226:229], v[20:23]
	v_mfma_f32_16x16x32_bf16 v[16:19], v[182:185], v[226:229], v[16:19]
	v_mfma_f32_16x16x32_bf16 v[4:7], v[174:177], v[234:237], v[4:7]
	v_mfma_f32_16x16x32_bf16 v[0:3], v[182:185], v[234:237], v[0:3]
	s_barrier
	s_add_i32 vcc_lo, vcc_lo, 2
	s_add_u32 s60, s60, 0x100
	s_addc_u32 s61, s61, 0
	s_add_u32 s96, s96, 0x100
	s_addc_u32 s97, s97, 0
	s_cmp_gt_u32 vcc_lo, 13
	s_cbranch_scc0 .LBB0_167
	v_mov_b32_e32 v142, v192
	s_lshl_b32 s11, s67, 8
	s_mov_b64 s[60:61], -1
	v_ashrrev_i32_e32 v143, 2, v142
	v_and_b32_e32 v143, 0xffffffc0, v143
	v_and_or_b32 v144, v142, 15, s11
	v_add_u32_e32 v146, v144, v143
	v_lshrrev_b32_e32 v142, 1, v142
	v_and_b32_e32 v142, 0x78, v142
	v_ashrrev_i32_e32 v147, 31, v146
	v_lshl_or_b32 v144, s66, 8, v142
	v_lshl_add_u64 v[142:143], v[146:147], 2, s[90:91]
	s_mov_b32 s11, 0x60000
	v_add_co_u32_e32 v148, vcc, s11, v142
	v_ashrrev_i32_e32 v145, 31, v144
	s_nop 0
	v_addc_co_u32_e32 v149, vcc, 0, v143, vcc
	global_load_dword v242, v[148:149], off
	global_load_dword v243, v[148:149], off offset:64
	global_load_dword v244, v[148:149], off offset:128
	global_load_dword v245, v[148:149], off offset:192
	global_load_dword v246, v[148:149], off offset:512
	global_load_dword v247, v[148:149], off offset:576
	global_load_dword v248, v[148:149], off offset:640
	global_load_dword v249, v[148:149], off offset:704
	s_and_b64 vcc, exec, s[6:7]
	s_cbranch_vccz .LBB0_170
	s_barrier
.LBB0_170:
	s_waitcnt vmcnt(7)
	v_fmamk_f32 v142, v242, 0x3a800000, v194
	v_cmp_gt_f32_e32 vcc, s19, v142
	v_mul_f32_e32 v143, 0x4b800000, v142
	s_nop 0
	v_cndmask_b32_e32 v142, v142, v143, vcc
	v_rsq_f32_e32 v142, v142
	s_nop 0
	v_mul_f32_e32 v143, 0x45800000, v142
	v_cndmask_b32_e32 v165, v142, v143, vcc
	v_lshlrev_b64 v[142:143], 11, v[146:147]
	v_lshl_add_u64 v[150:151], s[38:39], 0, v[142:143]
	v_lshl_add_u64 v[160:161], s[92:93], 0, v[142:143]
	v_lshlrev_b64 v[142:143], 1, v[144:145]
	v_lshl_add_u64 v[150:151], v[150:151], 0, v[142:143]
	v_lshl_add_u64 v[160:161], v[160:161], 0, v[142:143]
	global_load_dwordx4 v[166:169], v[150:151], off
	global_load_dwordx4 v[170:173], v[160:161], off
	v_mul_f32_e32 v126, v126, v165
	v_mul_f32_e32 v127, v127, v165
	v_mul_f32_e32 v126, 0xbfb8aa3b, v126
	v_mul_f32_e32 v122, v122, v165
	v_mul_f32_e32 v127, 0xbfb8aa3b, v127
	v_mul_f32_e32 v123, v123, v165
	v_exp_f32_e32 v126, v126
	v_mul_f32_e32 v122, 0xbfb8aa3b, v122
	v_exp_f32_e32 v127, v127
	v_mul_f32_e32 v123, 0xbfb8aa3b, v123
	v_mul_f32_e32 v128, v128, v165
	v_mul_f32_e32 v129, v129, v165
	v_exp_f32_e32 v122, v122
	v_exp_f32_e32 v123, v123
	v_mul_f32_e32 v128, 0xbfb8aa3b, v128
	v_mul_f32_e32 v124, v124, v165
	v_mul_f32_e32 v129, 0xbfb8aa3b, v129
	v_mul_f32_e32 v125, v125, v165
	v_exp_f32_e32 v128, v128
	v_mul_f32_e32 v124, 0xbfb8aa3b, v124
	v_exp_f32_e32 v129, v129
	v_mul_f32_e32 v125, 0xbfb8aa3b, v125
	v_exp_f32_e32 v124, v124
	v_exp_f32_e32 v125, v125
	v_add_f32_e32 v126, 1.0, v126
	v_add_f32_e32 v127, 1.0, v127
	v_rcp_f32_e32 v126, v126
	v_add_f32_e32 v122, 1.0, v122
	v_rcp_f32_e32 v127, v127
	v_add_f32_e32 v123, 1.0, v123
	v_rcp_f32_e32 v122, v122
	v_rcp_f32_e32 v123, v123
	v_add_f32_e32 v128, 1.0, v128
	v_add_f32_e32 v129, 1.0, v129
	v_rcp_f32_e32 v128, v128
	v_add_f32_e32 v124, 1.0, v124
	v_rcp_f32_e32 v129, v129
	v_add_f32_e32 v125, 1.0, v125
	v_rcp_f32_e32 v124, v124
	v_rcp_f32_e32 v125, v125
	v_lshlrev_b64 v[144:145], 2, v[144:145]
	v_mul_f32_e32 v118, v118, v165
	v_mul_f32_e32 v119, v119, v165
	v_mul_f32_e32 v120, v120, v165
	v_mul_f32_e32 v121, v121, v165
	v_mul_f32_e32 v118, 0xbfb8aa3b, v118
	v_mul_f32_e32 v114, v114, v165
	v_mul_f32_e32 v119, 0xbfb8aa3b, v119
	v_mul_f32_e32 v115, v115, v165
	v_mul_f32_e32 v120, 0xbfb8aa3b, v120
	v_mul_f32_e32 v116, v116, v165
	v_mul_f32_e32 v121, 0xbfb8aa3b, v121
	v_mul_f32_e32 v117, v117, v165
	v_exp_f32_e32 v118, v118
	v_mul_f32_e32 v114, 0xbfb8aa3b, v114
	v_exp_f32_e32 v119, v119
	v_mul_f32_e32 v115, 0xbfb8aa3b, v115
	v_exp_f32_e32 v120, v120
	v_mul_f32_e32 v116, 0xbfb8aa3b, v116
	v_exp_f32_e32 v121, v121
	v_mul_f32_e32 v117, 0xbfb8aa3b, v117
	v_exp_f32_e32 v114, v114
	v_exp_f32_e32 v115, v115
	v_exp_f32_e32 v116, v116
	v_exp_f32_e32 v117, v117
	v_add_f32_e32 v118, 1.0, v118
	v_add_f32_e32 v119, 1.0, v119
	v_add_f32_e32 v120, 1.0, v120
	v_add_f32_e32 v121, 1.0, v121
	v_rcp_f32_e32 v118, v118
	v_add_f32_e32 v114, 1.0, v114
	v_rcp_f32_e32 v119, v119
	v_add_f32_e32 v115, 1.0, v115
	v_rcp_f32_e32 v120, v120
	v_add_f32_e32 v116, 1.0, v116
	v_rcp_f32_e32 v121, v121
	v_add_f32_e32 v117, 1.0, v117
	v_rcp_f32_e32 v114, v114
	s_waitcnt vmcnt(1)
	v_lshlrev_b32_e32 v162, 16, v166
	v_and_b32_e32 v163, 0xffff0000, v166
	s_waitcnt vmcnt(0)
	v_lshlrev_b32_e32 v174, 16, v170
	v_and_b32_e32 v175, 0xffff0000, v170
	v_pk_fma_f32 v[126:127], v[126:127], v[174:175], v[162:163]
	v_lshlrev_b32_e32 v162, 16, v168
	v_and_b32_e32 v163, 0xffff0000, v168
	v_lshlrev_b32_e32 v174, 16, v172
	v_and_b32_e32 v175, 0xffff0000, v172
	v_pk_fma_f32 v[122:123], v[122:123], v[174:175], v[162:163]
	v_lshlrev_b32_e32 v162, 16, v167
	v_and_b32_e32 v163, 0xffff0000, v167
	v_lshlrev_b32_e32 v166, 16, v171
	v_and_b32_e32 v167, 0xffff0000, v171
	v_pk_fma_f32 v[128:129], v[128:129], v[166:167], v[162:163]
	v_lshlrev_b32_e32 v162, 16, v169
	v_and_b32_e32 v163, 0xffff0000, v169
	v_lshlrev_b32_e32 v166, 16, v173
	v_and_b32_e32 v167, 0xffff0000, v173
	v_pk_fma_f32 v[124:125], v[124:125], v[166:167], v[162:163]
	v_lshlrev_b64 v[162:163], 12, v[146:147]
	v_lshl_add_u64 v[162:163], s[88:89], 0, v[162:163]
	v_lshl_add_u64 v[162:163], v[162:163], 0, v[144:145]
	global_store_dwordx4 v[162:163], v[126:129], off
	global_store_dwordx4 v[162:163], v[122:125], off offset:16
	global_load_dwordx4 v[122:125], v[150:151], off offset:256
	s_nop 0
	global_load_dwordx4 v[126:129], v[160:161], off offset:256
	v_rcp_f32_e32 v115, v115
	v_rcp_f32_e32 v116, v116
	v_rcp_f32_e32 v117, v117
	s_waitcnt vmcnt(1)
	v_lshlrev_b32_e32 v150, 16, v122
	v_and_b32_e32 v151, 0xffff0000, v122
	s_waitcnt vmcnt(0)
	v_lshlrev_b32_e32 v160, 16, v126
	v_and_b32_e32 v161, 0xffff0000, v126
	v_lshlrev_b32_e32 v122, 16, v123
	v_and_b32_e32 v123, 0xffff0000, v123
	v_lshlrev_b32_e32 v126, 16, v127
	v_and_b32_e32 v127, 0xffff0000, v127
	v_pk_fma_f32 v[118:119], v[118:119], v[160:161], v[150:151]
	v_lshlrev_b32_e32 v150, 16, v124
	v_and_b32_e32 v151, 0xffff0000, v124
	v_lshlrev_b32_e32 v160, 16, v128
	v_and_b32_e32 v161, 0xffff0000, v128
	v_pk_fma_f32 v[120:121], v[120:121], v[126:127], v[122:123]
	v_lshlrev_b32_e32 v122, 16, v125
	v_and_b32_e32 v123, 0xffff0000, v125
	v_lshlrev_b32_e32 v124, 16, v129
	v_and_b32_e32 v125, 0xffff0000, v129
	v_pk_fma_f32 v[114:115], v[114:115], v[160:161], v[150:151]
	v_pk_fma_f32 v[116:117], v[116:117], v[124:125], v[122:123]
	global_store_dwordx4 v[162:163], v[118:121], off offset:512
	global_store_dwordx4 v[162:163], v[114:117], off offset:528
	s_nop 0
	s_nop 0
	v_or_b32_e32 v116, 16, v146
	v_ashrrev_i32_e32 v117, 31, v116
	s_waitcnt vmcnt(14)
	v_fmamk_f32 v114, v243, 0x3a800000, v194
	v_cmp_gt_f32_e32 vcc, s19, v114
	v_mul_f32_e32 v115, 0x4b800000, v114
	s_nop 0
	v_cndmask_b32_e32 v114, v114, v115, vcc
	v_rsq_f32_e32 v114, v114
	s_nop 0
	v_mul_f32_e32 v115, 0x45800000, v114
	v_cndmask_b32_e32 v120, v114, v115, vcc
	v_lshlrev_b64 v[114:115], 11, v[116:117]
	v_lshl_add_u64 v[122:123], s[38:39], 0, v[114:115]
	v_lshl_add_u64 v[118:119], s[92:93], 0, v[114:115]
	v_lshl_add_u64 v[114:115], v[122:123], 0, v[142:143]
	v_lshl_add_u64 v[118:119], v[118:119], 0, v[142:143]
	global_load_dwordx4 v[122:125], v[114:115], off
	global_load_dwordx4 v[126:129], v[118:119], off
	v_mul_f32_e32 v110, v110, v120
	v_mul_f32_e32 v111, v111, v120
	v_mul_f32_e32 v112, v112, v120
	v_mul_f32_e32 v113, v113, v120
	v_mul_f32_e32 v110, 0xbfb8aa3b, v110
	v_mul_f32_e32 v106, v106, v120
	v_mul_f32_e32 v111, 0xbfb8aa3b, v111
	v_mul_f32_e32 v107, v107, v120
	v_mul_f32_e32 v112, 0xbfb8aa3b, v112
	v_mul_f32_e32 v108, v108, v120
	v_mul_f32_e32 v113, 0xbfb8aa3b, v113
	v_mul_f32_e32 v109, v109, v120
	v_exp_f32_e32 v110, v110
	v_mul_f32_e32 v106, 0xbfb8aa3b, v106
	v_exp_f32_e32 v111, v111
	v_mul_f32_e32 v107, 0xbfb8aa3b, v107
	v_exp_f32_e32 v112, v112
	v_mul_f32_e32 v108, 0xbfb8aa3b, v108
	v_exp_f32_e32 v113, v113
	v_mul_f32_e32 v109, 0xbfb8aa3b, v109
	v_exp_f32_e32 v106, v106
	v_exp_f32_e32 v107, v107
	v_exp_f32_e32 v108, v108
	v_exp_f32_e32 v109, v109
	v_add_f32_e32 v110, 1.0, v110
	v_add_f32_e32 v111, 1.0, v111
	v_add_f32_e32 v112, 1.0, v112
	v_add_f32_e32 v113, 1.0, v113
	v_rcp_f32_e32 v110, v110
	v_add_f32_e32 v106, 1.0, v106
	v_rcp_f32_e32 v111, v111
	v_add_f32_e32 v107, 1.0, v107
	v_rcp_f32_e32 v112, v112
	v_add_f32_e32 v108, 1.0, v108
	v_rcp_f32_e32 v113, v113
	v_add_f32_e32 v109, 1.0, v109
	v_rcp_f32_e32 v106, v106
	v_rcp_f32_e32 v107, v107
	v_rcp_f32_e32 v108, v108
	v_rcp_f32_e32 v109, v109
	v_lshlrev_b64 v[116:117], 12, v[116:117]
	v_lshl_add_u64 v[116:117], s[88:89], 0, v[116:117]
	v_lshl_add_u64 v[116:117], v[116:117], 0, v[144:145]
	v_mul_f32_e32 v102, v102, v120
	v_mul_f32_e32 v103, v103, v120
	v_mul_f32_e32 v104, v104, v120
	v_mul_f32_e32 v105, v105, v120
	v_mul_f32_e32 v102, 0xbfb8aa3b, v102
	v_mul_f32_e32 v98, v98, v120
	v_mul_f32_e32 v103, 0xbfb8aa3b, v103
	v_mul_f32_e32 v99, v99, v120
	v_mul_f32_e32 v104, 0xbfb8aa3b, v104
	v_mul_f32_e32 v100, v100, v120
	v_mul_f32_e32 v105, 0xbfb8aa3b, v105
	v_mul_f32_e32 v101, v101, v120
	v_exp_f32_e32 v102, v102
	v_mul_f32_e32 v98, 0xbfb8aa3b, v98
	v_exp_f32_e32 v103, v103
	v_mul_f32_e32 v99, 0xbfb8aa3b, v99
	v_exp_f32_e32 v104, v104
	v_mul_f32_e32 v100, 0xbfb8aa3b, v100
	v_exp_f32_e32 v105, v105
	v_mul_f32_e32 v101, 0xbfb8aa3b, v101
	v_exp_f32_e32 v98, v98
	v_exp_f32_e32 v99, v99
	v_exp_f32_e32 v100, v100
	v_exp_f32_e32 v101, v101
	v_add_f32_e32 v102, 1.0, v102
	v_add_f32_e32 v103, 1.0, v103
	v_add_f32_e32 v104, 1.0, v104
	v_add_f32_e32 v105, 1.0, v105
	v_rcp_f32_e32 v102, v102
	v_add_f32_e32 v98, 1.0, v98
	v_rcp_f32_e32 v103, v103
	v_add_f32_e32 v99, 1.0, v99
	v_rcp_f32_e32 v104, v104
	v_add_f32_e32 v100, 1.0, v100
	v_rcp_f32_e32 v105, v105
	s_waitcnt vmcnt(1)
	v_lshlrev_b32_e32 v150, 16, v122
	v_and_b32_e32 v151, 0xffff0000, v122
	s_waitcnt vmcnt(0)
	v_lshlrev_b32_e32 v160, 16, v126
	v_and_b32_e32 v161, 0xffff0000, v126
	v_lshlrev_b32_e32 v122, 16, v123
	v_and_b32_e32 v123, 0xffff0000, v123
	v_lshlrev_b32_e32 v126, 16, v127
	v_and_b32_e32 v127, 0xffff0000, v127
	v_pk_fma_f32 v[110:111], v[110:111], v[160:161], v[150:151]
	v_lshlrev_b32_e32 v150, 16, v124
	v_and_b32_e32 v151, 0xffff0000, v124
	v_lshlrev_b32_e32 v160, 16, v128
	v_and_b32_e32 v161, 0xffff0000, v128
	v_pk_fma_f32 v[112:113], v[112:113], v[126:127], v[122:123]
	v_lshlrev_b32_e32 v122, 16, v125
	v_and_b32_e32 v123, 0xffff0000, v125
	v_lshlrev_b32_e32 v124, 16, v129
	v_and_b32_e32 v125, 0xffff0000, v129
	v_pk_fma_f32 v[106:107], v[106:107], v[160:161], v[150:151]
	v_pk_fma_f32 v[108:109], v[108:109], v[124:125], v[122:123]
	global_store_dwordx4 v[116:117], v[110:113], off
	global_store_dwordx4 v[116:117], v[106:109], off offset:16
	global_load_dwordx4 v[106:109], v[114:115], off offset:256
	s_nop 0
	global_load_dwordx4 v[110:113], v[118:119], off offset:256
	v_add_f32_e32 v101, 1.0, v101
	v_rcp_f32_e32 v98, v98
	v_rcp_f32_e32 v99, v99
	v_rcp_f32_e32 v100, v100
	v_rcp_f32_e32 v101, v101
	s_waitcnt vmcnt(1)
	v_lshlrev_b32_e32 v114, 16, v106
	v_and_b32_e32 v115, 0xffff0000, v106
	s_waitcnt vmcnt(0)
	v_lshlrev_b32_e32 v118, 16, v110
	v_and_b32_e32 v119, 0xffff0000, v110
	v_lshlrev_b32_e32 v106, 16, v107
	v_and_b32_e32 v107, 0xffff0000, v107
	v_lshlrev_b32_e32 v110, 16, v111
	v_and_b32_e32 v111, 0xffff0000, v111
	v_pk_fma_f32 v[102:103], v[102:103], v[118:119], v[114:115]
	v_lshlrev_b32_e32 v114, 16, v108
	v_and_b32_e32 v115, 0xffff0000, v108
	v_lshlrev_b32_e32 v118, 16, v112
	v_and_b32_e32 v119, 0xffff0000, v112
	v_pk_fma_f32 v[104:105], v[104:105], v[110:111], v[106:107]
	v_lshlrev_b32_e32 v106, 16, v109
	v_and_b32_e32 v107, 0xffff0000, v109
	v_lshlrev_b32_e32 v108, 16, v113
	v_and_b32_e32 v109, 0xffff0000, v113
	v_pk_fma_f32 v[98:99], v[98:99], v[118:119], v[114:115]
	v_pk_fma_f32 v[100:101], v[100:101], v[108:109], v[106:107]
	global_store_dwordx4 v[116:117], v[102:105], off offset:512
	global_store_dwordx4 v[116:117], v[98:101], off offset:528
	s_nop 0
	s_nop 0
	v_or_b32_e32 v100, 32, v146
	v_ashrrev_i32_e32 v101, 31, v100
	s_waitcnt vmcnt(21)
	v_fmamk_f32 v98, v244, 0x3a800000, v194
	v_cmp_gt_f32_e32 vcc, s19, v98
	v_mul_f32_e32 v99, 0x4b800000, v98
	s_nop 0
	v_cndmask_b32_e32 v98, v98, v99, vcc
	v_rsq_f32_e32 v98, v98
	s_nop 0
	v_mul_f32_e32 v99, 0x45800000, v98
	v_cndmask_b32_e32 v104, v98, v99, vcc
	v_lshlrev_b64 v[98:99], 11, v[100:101]
	v_lshl_add_u64 v[106:107], s[38:39], 0, v[98:99]
	v_lshl_add_u64 v[102:103], s[92:93], 0, v[98:99]
	v_lshl_add_u64 v[98:99], v[106:107], 0, v[142:143]
	v_lshl_add_u64 v[102:103], v[102:103], 0, v[142:143]
	global_load_dwordx4 v[106:109], v[98:99], off
	global_load_dwordx4 v[110:113], v[102:103], off
	v_mul_f32_e32 v94, v94, v104
	v_mul_f32_e32 v95, v95, v104
	v_mul_f32_e32 v96, v96, v104
	v_mul_f32_e32 v97, v97, v104
	v_mul_f32_e32 v94, 0xbfb8aa3b, v94
	v_mul_f32_e32 v90, v90, v104
	v_mul_f32_e32 v95, 0xbfb8aa3b, v95
	v_mul_f32_e32 v91, v91, v104
	v_mul_f32_e32 v96, 0xbfb8aa3b, v96
	v_mul_f32_e32 v92, v92, v104
	v_mul_f32_e32 v97, 0xbfb8aa3b, v97
	v_mul_f32_e32 v93, v93, v104
	v_exp_f32_e32 v94, v94
	v_mul_f32_e32 v90, 0xbfb8aa3b, v90
	v_exp_f32_e32 v95, v95
	v_mul_f32_e32 v91, 0xbfb8aa3b, v91
	v_exp_f32_e32 v96, v96
	v_mul_f32_e32 v92, 0xbfb8aa3b, v92
	v_exp_f32_e32 v97, v97
	v_mul_f32_e32 v93, 0xbfb8aa3b, v93
	v_exp_f32_e32 v90, v90
	v_exp_f32_e32 v91, v91
	v_exp_f32_e32 v92, v92
	v_exp_f32_e32 v93, v93
	v_add_f32_e32 v94, 1.0, v94
	v_add_f32_e32 v95, 1.0, v95
	v_add_f32_e32 v96, 1.0, v96
	v_add_f32_e32 v97, 1.0, v97
	v_rcp_f32_e32 v94, v94
	v_add_f32_e32 v90, 1.0, v90
	v_rcp_f32_e32 v95, v95
	v_add_f32_e32 v91, 1.0, v91
	v_rcp_f32_e32 v96, v96
	v_add_f32_e32 v92, 1.0, v92
	v_rcp_f32_e32 v97, v97
	v_add_f32_e32 v93, 1.0, v93
	v_rcp_f32_e32 v90, v90
	v_rcp_f32_e32 v91, v91
	v_rcp_f32_e32 v92, v92
	v_rcp_f32_e32 v93, v93
	v_lshlrev_b64 v[100:101], 12, v[100:101]
	v_lshl_add_u64 v[100:101], s[88:89], 0, v[100:101]
	v_lshl_add_u64 v[100:101], v[100:101], 0, v[144:145]
	v_mul_f32_e32 v86, v86, v104
	v_mul_f32_e32 v87, v87, v104
	v_mul_f32_e32 v88, v88, v104
	v_mul_f32_e32 v89, v89, v104
	v_mul_f32_e32 v86, 0xbfb8aa3b, v86
	v_mul_f32_e32 v82, v82, v104
	v_mul_f32_e32 v87, 0xbfb8aa3b, v87
	v_mul_f32_e32 v83, v83, v104
	v_mul_f32_e32 v88, 0xbfb8aa3b, v88
	v_mul_f32_e32 v84, v84, v104
	v_mul_f32_e32 v89, 0xbfb8aa3b, v89
	v_mul_f32_e32 v85, v85, v104
	v_exp_f32_e32 v86, v86
	v_mul_f32_e32 v82, 0xbfb8aa3b, v82
	v_exp_f32_e32 v87, v87
	v_mul_f32_e32 v83, 0xbfb8aa3b, v83
	v_exp_f32_e32 v88, v88
	v_mul_f32_e32 v84, 0xbfb8aa3b, v84
	v_exp_f32_e32 v89, v89
	v_mul_f32_e32 v85, 0xbfb8aa3b, v85
	v_exp_f32_e32 v82, v82
	v_exp_f32_e32 v83, v83
	v_exp_f32_e32 v84, v84
	v_exp_f32_e32 v85, v85
	v_add_f32_e32 v86, 1.0, v86
	v_add_f32_e32 v87, 1.0, v87
	v_add_f32_e32 v88, 1.0, v88
	v_add_f32_e32 v89, 1.0, v89
	v_rcp_f32_e32 v86, v86
	v_add_f32_e32 v82, 1.0, v82
	v_rcp_f32_e32 v87, v87
	v_add_f32_e32 v83, 1.0, v83
	v_rcp_f32_e32 v88, v88
	v_add_f32_e32 v84, 1.0, v84
	v_rcp_f32_e32 v89, v89
	s_waitcnt vmcnt(1)
	v_lshlrev_b32_e32 v114, 16, v106
	v_and_b32_e32 v115, 0xffff0000, v106
	s_waitcnt vmcnt(0)
	v_lshlrev_b32_e32 v116, 16, v110
	v_and_b32_e32 v117, 0xffff0000, v110
	v_lshlrev_b32_e32 v106, 16, v107
	v_and_b32_e32 v107, 0xffff0000, v107
	v_lshlrev_b32_e32 v110, 16, v111
	v_and_b32_e32 v111, 0xffff0000, v111
	v_pk_fma_f32 v[94:95], v[94:95], v[116:117], v[114:115]
	v_lshlrev_b32_e32 v114, 16, v108
	v_and_b32_e32 v115, 0xffff0000, v108
	v_lshlrev_b32_e32 v116, 16, v112
	v_and_b32_e32 v117, 0xffff0000, v112
	v_pk_fma_f32 v[96:97], v[96:97], v[110:111], v[106:107]
	v_lshlrev_b32_e32 v106, 16, v109
	v_and_b32_e32 v107, 0xffff0000, v109
	v_lshlrev_b32_e32 v108, 16, v113
	v_and_b32_e32 v109, 0xffff0000, v113
	v_pk_fma_f32 v[90:91], v[90:91], v[116:117], v[114:115]
	v_pk_fma_f32 v[92:93], v[92:93], v[108:109], v[106:107]
	global_store_dwordx4 v[100:101], v[94:97], off
	global_store_dwordx4 v[100:101], v[90:93], off offset:16
	global_load_dwordx4 v[90:93], v[98:99], off offset:256
	s_nop 0
	global_load_dwordx4 v[94:97], v[102:103], off offset:256
	v_add_f32_e32 v85, 1.0, v85
	v_rcp_f32_e32 v82, v82
	v_rcp_f32_e32 v83, v83
	v_rcp_f32_e32 v84, v84
	v_rcp_f32_e32 v85, v85
	s_waitcnt vmcnt(1)
	v_lshlrev_b32_e32 v98, 16, v90
	v_and_b32_e32 v99, 0xffff0000, v90
	s_waitcnt vmcnt(0)
	v_lshlrev_b32_e32 v102, 16, v94
	v_and_b32_e32 v103, 0xffff0000, v94
	v_lshlrev_b32_e32 v90, 16, v91
	v_and_b32_e32 v91, 0xffff0000, v91
	v_lshlrev_b32_e32 v94, 16, v95
	v_and_b32_e32 v95, 0xffff0000, v95
	v_pk_fma_f32 v[86:87], v[86:87], v[102:103], v[98:99]
	v_lshlrev_b32_e32 v98, 16, v92
	v_and_b32_e32 v99, 0xffff0000, v92
	v_lshlrev_b32_e32 v102, 16, v96
	v_and_b32_e32 v103, 0xffff0000, v96
	v_pk_fma_f32 v[88:89], v[88:89], v[94:95], v[90:91]
	v_lshlrev_b32_e32 v90, 16, v93
	v_and_b32_e32 v91, 0xffff0000, v93
	v_lshlrev_b32_e32 v92, 16, v97
	v_and_b32_e32 v93, 0xffff0000, v97
	v_pk_fma_f32 v[82:83], v[82:83], v[102:103], v[98:99]
	v_pk_fma_f32 v[84:85], v[84:85], v[92:93], v[90:91]
	global_store_dwordx4 v[100:101], v[86:89], off offset:512
	global_store_dwordx4 v[100:101], v[82:85], off offset:528
	s_nop 0
	s_nop 0
	v_or_b32_e32 v84, 48, v146
	v_ashrrev_i32_e32 v85, 31, v84
	s_waitcnt vmcnt(28)
	v_fmamk_f32 v82, v245, 0x3a800000, v194
	v_cmp_gt_f32_e32 vcc, s19, v82
	v_mul_f32_e32 v83, 0x4b800000, v82
	s_nop 0
	v_cndmask_b32_e32 v82, v82, v83, vcc
	v_rsq_f32_e32 v82, v82
	s_nop 0
	v_mul_f32_e32 v83, 0x45800000, v82
	v_cndmask_b32_e32 v88, v82, v83, vcc
	v_lshlrev_b64 v[82:83], 11, v[84:85]
	v_lshl_add_u64 v[90:91], s[38:39], 0, v[82:83]
	v_lshl_add_u64 v[86:87], s[92:93], 0, v[82:83]
	v_lshl_add_u64 v[82:83], v[90:91], 0, v[142:143]
	v_lshl_add_u64 v[86:87], v[86:87], 0, v[142:143]
	global_load_dwordx4 v[90:93], v[82:83], off
	global_load_dwordx4 v[94:97], v[86:87], off
	v_mul_f32_e32 v76, v76, v88
	v_mul_f32_e32 v77, v77, v88
	v_mul_f32_e32 v78, v78, v88
	v_mul_f32_e32 v79, v79, v88
	v_mul_f32_e32 v76, 0xbfb8aa3b, v76
	v_mul_f32_e32 v72, v72, v88
	v_mul_f32_e32 v77, 0xbfb8aa3b, v77
	v_mul_f32_e32 v73, v73, v88
	v_mul_f32_e32 v78, 0xbfb8aa3b, v78
	v_mul_f32_e32 v74, v74, v88
	v_mul_f32_e32 v79, 0xbfb8aa3b, v79
	v_mul_f32_e32 v75, v75, v88
	v_exp_f32_e32 v76, v76
	v_mul_f32_e32 v72, 0xbfb8aa3b, v72
	v_exp_f32_e32 v77, v77
	v_mul_f32_e32 v73, 0xbfb8aa3b, v73
	v_exp_f32_e32 v78, v78
	v_mul_f32_e32 v74, 0xbfb8aa3b, v74
	v_exp_f32_e32 v79, v79
	v_mul_f32_e32 v75, 0xbfb8aa3b, v75
	v_exp_f32_e32 v72, v72
	v_exp_f32_e32 v73, v73
	v_exp_f32_e32 v74, v74
	v_exp_f32_e32 v75, v75
	v_add_f32_e32 v76, 1.0, v76
	v_add_f32_e32 v77, 1.0, v77
	v_add_f32_e32 v78, 1.0, v78
	v_add_f32_e32 v79, 1.0, v79
	v_rcp_f32_e32 v76, v76
	v_add_f32_e32 v72, 1.0, v72
	v_rcp_f32_e32 v77, v77
	v_add_f32_e32 v73, 1.0, v73
	v_rcp_f32_e32 v78, v78
	v_add_f32_e32 v74, 1.0, v74
	v_rcp_f32_e32 v79, v79
	v_add_f32_e32 v75, 1.0, v75
	v_rcp_f32_e32 v72, v72
	v_rcp_f32_e32 v73, v73
	v_rcp_f32_e32 v74, v74
	v_rcp_f32_e32 v75, v75
	v_lshlrev_b64 v[84:85], 12, v[84:85]
	v_lshl_add_u64 v[84:85], s[88:89], 0, v[84:85]
	v_lshl_add_u64 v[84:85], v[84:85], 0, v[144:145]
	v_mul_f32_e32 v68, v68, v88
	v_mul_f32_e32 v69, v69, v88
	v_mul_f32_e32 v70, v70, v88
	v_mul_f32_e32 v71, v71, v88
	v_mul_f32_e32 v68, 0xbfb8aa3b, v68
	v_mul_f32_e32 v69, 0xbfb8aa3b, v69
	v_mul_f32_e32 v70, 0xbfb8aa3b, v70
	v_mul_f32_e32 v66, v66, v88
	v_mul_f32_e32 v71, 0xbfb8aa3b, v71
	v_mul_f32_e32 v67, v67, v88
	v_exp_f32_e32 v68, v68
	v_mul_f32_e32 v64, v64, v88
	v_exp_f32_e32 v69, v69
	v_mul_f32_e32 v65, v65, v88
	v_exp_f32_e32 v70, v70
	v_mul_f32_e32 v66, 0xbfb8aa3b, v66
	v_exp_f32_e32 v71, v71
	v_mul_f32_e32 v67, 0xbfb8aa3b, v67
	v_mul_f32_e32 v64, 0xbfb8aa3b, v64
	v_mul_f32_e32 v65, 0xbfb8aa3b, v65
	v_exp_f32_e32 v66, v66
	v_exp_f32_e32 v67, v67
	v_exp_f32_e32 v64, v64
	v_exp_f32_e32 v65, v65
	v_add_f32_e32 v68, 1.0, v68
	v_add_f32_e32 v69, 1.0, v69
	v_add_f32_e32 v70, 1.0, v70
	v_add_f32_e32 v71, 1.0, v71
	v_rcp_f32_e32 v68, v68
	v_rcp_f32_e32 v69, v69
	v_rcp_f32_e32 v70, v70
	v_add_f32_e32 v66, 1.0, v66
	v_rcp_f32_e32 v71, v71
	v_add_f32_e32 v67, 1.0, v67
	v_add_f32_e32 v64, 1.0, v64
	s_waitcnt vmcnt(1)
	v_lshlrev_b32_e32 v98, 16, v90
	v_and_b32_e32 v99, 0xffff0000, v90
	s_waitcnt vmcnt(0)
	v_lshlrev_b32_e32 v100, 16, v94
	v_and_b32_e32 v101, 0xffff0000, v94
	v_lshlrev_b32_e32 v90, 16, v91
	v_and_b32_e32 v91, 0xffff0000, v91
	v_lshlrev_b32_e32 v94, 16, v95
	v_and_b32_e32 v95, 0xffff0000, v95
	v_pk_fma_f32 v[76:77], v[76:77], v[100:101], v[98:99]
	v_lshlrev_b32_e32 v98, 16, v92
	v_and_b32_e32 v99, 0xffff0000, v92
	v_lshlrev_b32_e32 v100, 16, v96
	v_and_b32_e32 v101, 0xffff0000, v96
	v_pk_fma_f32 v[78:79], v[78:79], v[94:95], v[90:91]
	v_lshlrev_b32_e32 v90, 16, v93
	v_and_b32_e32 v91, 0xffff0000, v93
	v_lshlrev_b32_e32 v92, 16, v97
	v_and_b32_e32 v93, 0xffff0000, v97
	v_pk_fma_f32 v[72:73], v[72:73], v[100:101], v[98:99]
	v_pk_fma_f32 v[74:75], v[74:75], v[92:93], v[90:91]
	global_store_dwordx4 v[84:85], v[76:79], off
	global_store_dwordx4 v[84:85], v[72:75], off offset:16
	global_load_dwordx4 v[72:75], v[82:83], off offset:256
	s_nop 0
	global_load_dwordx4 v[76:79], v[86:87], off offset:256
	v_add_f32_e32 v65, 1.0, v65
	v_rcp_f32_e32 v66, v66
	v_rcp_f32_e32 v67, v67
	v_rcp_f32_e32 v64, v64
	v_rcp_f32_e32 v65, v65
	s_waitcnt vmcnt(1)
	v_lshlrev_b32_e32 v82, 16, v72
	v_and_b32_e32 v83, 0xffff0000, v72
	s_waitcnt vmcnt(0)
	v_lshlrev_b32_e32 v86, 16, v76
	v_and_b32_e32 v87, 0xffff0000, v76
	v_lshlrev_b32_e32 v72, 16, v73
	v_and_b32_e32 v73, 0xffff0000, v73
	v_lshlrev_b32_e32 v76, 16, v77
	v_and_b32_e32 v77, 0xffff0000, v77
	v_pk_fma_f32 v[68:69], v[68:69], v[86:87], v[82:83]
	v_lshlrev_b32_e32 v82, 16, v74
	v_and_b32_e32 v83, 0xffff0000, v74
	v_pk_fma_f32 v[70:71], v[70:71], v[76:77], v[72:73]
	v_lshlrev_b32_e32 v72, 16, v75
	v_and_b32_e32 v73, 0xffff0000, v75
	v_lshlrev_b32_e32 v74, 16, v79
	v_and_b32_e32 v75, 0xffff0000, v79
	v_lshlrev_b32_e32 v86, 16, v78
	v_and_b32_e32 v87, 0xffff0000, v78
	v_pk_fma_f32 v[66:67], v[66:67], v[74:75], v[72:73]
	v_pk_fma_f32 v[64:65], v[64:65], v[86:87], v[82:83]
	global_store_dwordx4 v[84:85], v[68:71], off offset:512
	global_store_dwordx4 v[84:85], v[64:67], off offset:528
	s_nop 1
	v_add_u32_e32 v66, 0x80, v146
	v_ashrrev_i32_e32 v67, 31, v66
	v_lshl_add_u64 v[64:65], v[66:67], 2, s[90:91]
	v_add_co_u32_e32 v64, vcc, s11, v64
	s_nop 1
	v_addc_co_u32_e32 v65, vcc, 0, v65, vcc
	s_nop 0
	s_waitcnt vmcnt(35)
	v_fmamk_f32 v64, v246, 0x3a800000, v194
	v_cmp_gt_f32_e32 vcc, s19, v64
	v_mul_f32_e32 v65, 0x4b800000, v64
	s_nop 0
	v_cndmask_b32_e32 v64, v64, v65, vcc
	v_rsq_f32_e32 v64, v64
	s_nop 0
	v_mul_f32_e32 v65, 0x45800000, v64
	v_cndmask_b32_e32 v70, v64, v65, vcc
	v_lshlrev_b64 v[64:65], 11, v[66:67]
	v_lshl_add_u64 v[72:73], s[38:39], 0, v[64:65]
	v_lshl_add_u64 v[68:69], s[92:93], 0, v[64:65]
	v_lshl_add_u64 v[64:65], v[72:73], 0, v[142:143]
	v_lshl_add_u64 v[68:69], v[68:69], 0, v[142:143]
	global_load_dwordx4 v[72:75], v[64:65], off
	global_load_dwordx4 v[76:79], v[68:69], off
	v_mul_f32_e32 v60, v60, v70
	v_mul_f32_e32 v61, v61, v70
	v_mul_f32_e32 v62, v62, v70
	v_mul_f32_e32 v63, v63, v70
	v_mul_f32_e32 v60, 0xbfb8aa3b, v60
	v_mul_f32_e32 v56, v56, v70
	v_mul_f32_e32 v61, 0xbfb8aa3b, v61
	v_mul_f32_e32 v57, v57, v70
	v_mul_f32_e32 v62, 0xbfb8aa3b, v62
	v_mul_f32_e32 v58, v58, v70
	v_mul_f32_e32 v63, 0xbfb8aa3b, v63
	v_mul_f32_e32 v59, v59, v70
	v_exp_f32_e32 v60, v60
	v_mul_f32_e32 v56, 0xbfb8aa3b, v56
	v_exp_f32_e32 v61, v61
	v_mul_f32_e32 v57, 0xbfb8aa3b, v57
	v_exp_f32_e32 v62, v62
	v_mul_f32_e32 v58, 0xbfb8aa3b, v58
	v_exp_f32_e32 v63, v63
	v_mul_f32_e32 v59, 0xbfb8aa3b, v59
	v_exp_f32_e32 v56, v56
	v_exp_f32_e32 v57, v57
	v_exp_f32_e32 v58, v58
	v_exp_f32_e32 v59, v59
	v_add_f32_e32 v60, 1.0, v60
	v_add_f32_e32 v61, 1.0, v61
	v_add_f32_e32 v62, 1.0, v62
	v_add_f32_e32 v63, 1.0, v63
	v_rcp_f32_e32 v60, v60
	v_add_f32_e32 v56, 1.0, v56
	v_rcp_f32_e32 v61, v61
	v_add_f32_e32 v57, 1.0, v57
	v_rcp_f32_e32 v62, v62
	v_add_f32_e32 v58, 1.0, v58
	v_rcp_f32_e32 v63, v63
	v_add_f32_e32 v59, 1.0, v59
	v_rcp_f32_e32 v56, v56
	v_rcp_f32_e32 v57, v57
	v_rcp_f32_e32 v58, v58
	v_rcp_f32_e32 v59, v59
	v_lshlrev_b64 v[66:67], 12, v[66:67]
	v_lshl_add_u64 v[66:67], s[88:89], 0, v[66:67]
	v_lshl_add_u64 v[66:67], v[66:67], 0, v[144:145]
	v_mul_f32_e32 v52, v52, v70
	v_mul_f32_e32 v53, v53, v70
	v_mul_f32_e32 v54, v54, v70
	v_mul_f32_e32 v55, v55, v70
	v_mul_f32_e32 v52, 0xbfb8aa3b, v52
	v_mul_f32_e32 v53, 0xbfb8aa3b, v53
	v_mul_f32_e32 v54, 0xbfb8aa3b, v54
	v_mul_f32_e32 v50, v50, v70
	v_mul_f32_e32 v55, 0xbfb8aa3b, v55
	v_mul_f32_e32 v51, v51, v70
	v_exp_f32_e32 v52, v52
	v_mul_f32_e32 v48, v48, v70
	v_exp_f32_e32 v53, v53
	v_mul_f32_e32 v49, v49, v70
	v_exp_f32_e32 v54, v54
	v_mul_f32_e32 v50, 0xbfb8aa3b, v50
	v_exp_f32_e32 v55, v55
	v_mul_f32_e32 v51, 0xbfb8aa3b, v51
	v_mul_f32_e32 v48, 0xbfb8aa3b, v48
	v_mul_f32_e32 v49, 0xbfb8aa3b, v49
	v_exp_f32_e32 v50, v50
	v_exp_f32_e32 v51, v51
	v_exp_f32_e32 v48, v48
	v_exp_f32_e32 v49, v49
	v_add_f32_e32 v52, 1.0, v52
	v_add_f32_e32 v53, 1.0, v53
	v_add_f32_e32 v54, 1.0, v54
	v_add_f32_e32 v55, 1.0, v55
	v_rcp_f32_e32 v52, v52
	v_rcp_f32_e32 v53, v53
	v_rcp_f32_e32 v54, v54
	v_add_f32_e32 v50, 1.0, v50
	v_rcp_f32_e32 v55, v55
	v_add_f32_e32 v51, 1.0, v51
	v_add_f32_e32 v48, 1.0, v48
	s_waitcnt vmcnt(1)
	v_lshlrev_b32_e32 v82, 16, v72
	v_and_b32_e32 v83, 0xffff0000, v72
	s_waitcnt vmcnt(0)
	v_lshlrev_b32_e32 v84, 16, v76
	v_and_b32_e32 v85, 0xffff0000, v76
	v_lshlrev_b32_e32 v72, 16, v73
	v_and_b32_e32 v73, 0xffff0000, v73
	v_lshlrev_b32_e32 v76, 16, v77
	v_and_b32_e32 v77, 0xffff0000, v77
	v_pk_fma_f32 v[60:61], v[60:61], v[84:85], v[82:83]
	v_lshlrev_b32_e32 v82, 16, v74
	v_and_b32_e32 v83, 0xffff0000, v74
	v_lshlrev_b32_e32 v84, 16, v78
	v_and_b32_e32 v85, 0xffff0000, v78
	v_pk_fma_f32 v[62:63], v[62:63], v[76:77], v[72:73]
	v_lshlrev_b32_e32 v72, 16, v75
	v_and_b32_e32 v73, 0xffff0000, v75
	v_lshlrev_b32_e32 v74, 16, v79
	v_and_b32_e32 v75, 0xffff0000, v79
	v_pk_fma_f32 v[56:57], v[56:57], v[84:85], v[82:83]
	v_pk_fma_f32 v[58:59], v[58:59], v[74:75], v[72:73]
	global_store_dwordx4 v[66:67], v[60:63], off
	global_store_dwordx4 v[66:67], v[56:59], off offset:16
	global_load_dwordx4 v[56:59], v[64:65], off offset:256
	s_nop 0
	global_load_dwordx4 v[60:63], v[68:69], off offset:256
	v_add_f32_e32 v49, 1.0, v49
	v_rcp_f32_e32 v50, v50
	v_rcp_f32_e32 v51, v51
	v_rcp_f32_e32 v48, v48
	v_rcp_f32_e32 v49, v49
	s_waitcnt vmcnt(1)
	v_lshlrev_b32_e32 v64, 16, v56
	v_and_b32_e32 v65, 0xffff0000, v56
	s_waitcnt vmcnt(0)
	v_lshlrev_b32_e32 v68, 16, v60
	v_and_b32_e32 v69, 0xffff0000, v60
	v_lshlrev_b32_e32 v56, 16, v57
	v_and_b32_e32 v57, 0xffff0000, v57
	v_lshlrev_b32_e32 v60, 16, v61
	v_and_b32_e32 v61, 0xffff0000, v61
	v_pk_fma_f32 v[52:53], v[52:53], v[68:69], v[64:65]
	v_lshlrev_b32_e32 v64, 16, v58
	v_and_b32_e32 v65, 0xffff0000, v58
	v_pk_fma_f32 v[54:55], v[54:55], v[60:61], v[56:57]
	v_lshlrev_b32_e32 v56, 16, v59
	v_and_b32_e32 v57, 0xffff0000, v59
	v_lshlrev_b32_e32 v58, 16, v63
	v_and_b32_e32 v59, 0xffff0000, v63
	v_lshlrev_b32_e32 v68, 16, v62
	v_and_b32_e32 v69, 0xffff0000, v62
	v_pk_fma_f32 v[50:51], v[50:51], v[58:59], v[56:57]
	v_pk_fma_f32 v[48:49], v[48:49], v[68:69], v[64:65]
	global_store_dwordx4 v[66:67], v[52:55], off offset:512
	global_store_dwordx4 v[66:67], v[48:51], off offset:528
	s_nop 1
	v_add_u32_e32 v50, 0x90, v146
	v_ashrrev_i32_e32 v51, 31, v50
	v_lshl_add_u64 v[48:49], v[50:51], 2, s[90:91]
	v_add_co_u32_e32 v48, vcc, s11, v48
	s_nop 1
	v_addc_co_u32_e32 v49, vcc, 0, v49, vcc
	s_nop 0
	s_waitcnt vmcnt(42)
	v_fmamk_f32 v48, v247, 0x3a800000, v194
	v_cmp_gt_f32_e32 vcc, s19, v48
	v_mul_f32_e32 v49, 0x4b800000, v48
	s_nop 0
	v_cndmask_b32_e32 v48, v48, v49, vcc
	v_rsq_f32_e32 v48, v48
	s_nop 0
	v_mul_f32_e32 v49, 0x45800000, v48
	v_cndmask_b32_e32 v54, v48, v49, vcc
	v_lshlrev_b64 v[48:49], 11, v[50:51]
	v_lshl_add_u64 v[56:57], s[38:39], 0, v[48:49]
	v_lshl_add_u64 v[52:53], s[92:93], 0, v[48:49]
	v_lshl_add_u64 v[48:49], v[56:57], 0, v[142:143]
	v_lshl_add_u64 v[52:53], v[52:53], 0, v[142:143]
	global_load_dwordx4 v[56:59], v[48:49], off
	global_load_dwordx4 v[60:63], v[52:53], off
	v_mul_f32_e32 v44, v44, v54
	v_mul_f32_e32 v45, v45, v54
	v_mul_f32_e32 v46, v46, v54
	v_mul_f32_e32 v47, v47, v54
	v_mul_f32_e32 v44, 0xbfb8aa3b, v44
	v_mul_f32_e32 v40, v40, v54
	v_mul_f32_e32 v45, 0xbfb8aa3b, v45
	v_mul_f32_e32 v41, v41, v54
	v_mul_f32_e32 v46, 0xbfb8aa3b, v46
	v_mul_f32_e32 v42, v42, v54
	v_mul_f32_e32 v47, 0xbfb8aa3b, v47
	v_mul_f32_e32 v43, v43, v54
	v_exp_f32_e32 v44, v44
	v_mul_f32_e32 v40, 0xbfb8aa3b, v40
	v_exp_f32_e32 v45, v45
	v_mul_f32_e32 v41, 0xbfb8aa3b, v41
	v_exp_f32_e32 v46, v46
	v_mul_f32_e32 v42, 0xbfb8aa3b, v42
	v_exp_f32_e32 v47, v47
	v_mul_f32_e32 v43, 0xbfb8aa3b, v43
	v_exp_f32_e32 v40, v40
	v_exp_f32_e32 v41, v41
	v_exp_f32_e32 v42, v42
	v_exp_f32_e32 v43, v43
	v_add_f32_e32 v44, 1.0, v44
	v_add_f32_e32 v45, 1.0, v45
	v_add_f32_e32 v46, 1.0, v46
	v_add_f32_e32 v47, 1.0, v47
	v_rcp_f32_e32 v44, v44
	v_add_f32_e32 v40, 1.0, v40
	v_rcp_f32_e32 v45, v45
	v_add_f32_e32 v41, 1.0, v41
	v_rcp_f32_e32 v46, v46
	v_add_f32_e32 v42, 1.0, v42
	v_rcp_f32_e32 v47, v47
	v_add_f32_e32 v43, 1.0, v43
	v_rcp_f32_e32 v40, v40
	v_rcp_f32_e32 v41, v41
	v_rcp_f32_e32 v42, v42
	v_rcp_f32_e32 v43, v43
	v_lshlrev_b64 v[50:51], 12, v[50:51]
	v_lshl_add_u64 v[50:51], s[88:89], 0, v[50:51]
	v_lshl_add_u64 v[50:51], v[50:51], 0, v[144:145]
	v_mul_f32_e32 v36, v36, v54
	v_mul_f32_e32 v37, v37, v54
	v_mul_f32_e32 v38, v38, v54
	v_mul_f32_e32 v39, v39, v54
	v_mul_f32_e32 v36, 0xbfb8aa3b, v36
	v_mul_f32_e32 v37, 0xbfb8aa3b, v37
	v_mul_f32_e32 v38, 0xbfb8aa3b, v38
	v_mul_f32_e32 v34, v34, v54
	v_mul_f32_e32 v39, 0xbfb8aa3b, v39
	v_mul_f32_e32 v35, v35, v54
	v_exp_f32_e32 v36, v36
	v_mul_f32_e32 v32, v32, v54
	v_exp_f32_e32 v37, v37
	v_mul_f32_e32 v33, v33, v54
	v_exp_f32_e32 v38, v38
	v_mul_f32_e32 v34, 0xbfb8aa3b, v34
	v_exp_f32_e32 v39, v39
	v_mul_f32_e32 v35, 0xbfb8aa3b, v35
	v_mul_f32_e32 v32, 0xbfb8aa3b, v32
	v_mul_f32_e32 v33, 0xbfb8aa3b, v33
	v_exp_f32_e32 v34, v34
	v_exp_f32_e32 v35, v35
	v_exp_f32_e32 v32, v32
	v_exp_f32_e32 v33, v33
	v_add_f32_e32 v36, 1.0, v36
	v_add_f32_e32 v37, 1.0, v37
	v_add_f32_e32 v38, 1.0, v38
	v_add_f32_e32 v39, 1.0, v39
	v_rcp_f32_e32 v36, v36
	v_rcp_f32_e32 v37, v37
	v_rcp_f32_e32 v38, v38
	v_add_f32_e32 v34, 1.0, v34
	v_rcp_f32_e32 v39, v39
	v_add_f32_e32 v35, 1.0, v35
	v_add_f32_e32 v32, 1.0, v32
	s_waitcnt vmcnt(1)
	v_lshlrev_b32_e32 v64, 16, v56
	v_and_b32_e32 v65, 0xffff0000, v56
	s_waitcnt vmcnt(0)
	v_lshlrev_b32_e32 v66, 16, v60
	v_and_b32_e32 v67, 0xffff0000, v60
	v_lshlrev_b32_e32 v56, 16, v57
	v_and_b32_e32 v57, 0xffff0000, v57
	v_lshlrev_b32_e32 v60, 16, v61
	v_and_b32_e32 v61, 0xffff0000, v61
	v_pk_fma_f32 v[44:45], v[44:45], v[66:67], v[64:65]
	v_lshlrev_b32_e32 v64, 16, v58
	v_and_b32_e32 v65, 0xffff0000, v58
	v_lshlrev_b32_e32 v66, 16, v62
	v_and_b32_e32 v67, 0xffff0000, v62
	v_pk_fma_f32 v[46:47], v[46:47], v[60:61], v[56:57]
	v_lshlrev_b32_e32 v56, 16, v59
	v_and_b32_e32 v57, 0xffff0000, v59
	v_lshlrev_b32_e32 v58, 16, v63
	v_and_b32_e32 v59, 0xffff0000, v63
	v_pk_fma_f32 v[40:41], v[40:41], v[66:67], v[64:65]
	v_pk_fma_f32 v[42:43], v[42:43], v[58:59], v[56:57]
	global_store_dwordx4 v[50:51], v[44:47], off
	global_store_dwordx4 v[50:51], v[40:43], off offset:16
	global_load_dwordx4 v[40:43], v[48:49], off offset:256
	s_nop 0
	global_load_dwordx4 v[44:47], v[52:53], off offset:256
	v_add_f32_e32 v33, 1.0, v33
	v_rcp_f32_e32 v34, v34
	v_rcp_f32_e32 v35, v35
	v_rcp_f32_e32 v32, v32
	v_rcp_f32_e32 v33, v33
	s_waitcnt vmcnt(1)
	v_lshlrev_b32_e32 v48, 16, v40
	v_and_b32_e32 v49, 0xffff0000, v40
	s_waitcnt vmcnt(0)
	v_lshlrev_b32_e32 v52, 16, v44
	v_and_b32_e32 v53, 0xffff0000, v44
	v_lshlrev_b32_e32 v40, 16, v41
	v_and_b32_e32 v41, 0xffff0000, v41
	v_lshlrev_b32_e32 v44, 16, v45
	v_and_b32_e32 v45, 0xffff0000, v45
	v_pk_fma_f32 v[36:37], v[36:37], v[52:53], v[48:49]
	v_lshlrev_b32_e32 v48, 16, v42
	v_and_b32_e32 v49, 0xffff0000, v42
	v_pk_fma_f32 v[38:39], v[38:39], v[44:45], v[40:41]
	v_lshlrev_b32_e32 v40, 16, v43
	v_and_b32_e32 v41, 0xffff0000, v43
	v_lshlrev_b32_e32 v42, 16, v47
	v_and_b32_e32 v43, 0xffff0000, v47
	v_lshlrev_b32_e32 v52, 16, v46
	v_and_b32_e32 v53, 0xffff0000, v46
	v_pk_fma_f32 v[34:35], v[34:35], v[42:43], v[40:41]
	v_pk_fma_f32 v[32:33], v[32:33], v[52:53], v[48:49]
	global_store_dwordx4 v[50:51], v[36:39], off offset:512
	global_store_dwordx4 v[50:51], v[32:35], off offset:528
	s_nop 1
	v_add_u32_e32 v34, 0xa0, v146
	v_ashrrev_i32_e32 v35, 31, v34
	v_lshl_add_u64 v[32:33], v[34:35], 2, s[90:91]
	v_add_co_u32_e32 v32, vcc, s11, v32
	s_nop 1
	v_addc_co_u32_e32 v33, vcc, 0, v33, vcc
	s_nop 0
	s_waitcnt vmcnt(49)
	v_fmamk_f32 v32, v248, 0x3a800000, v194
	v_cmp_gt_f32_e32 vcc, s19, v32
	v_mul_f32_e32 v33, 0x4b800000, v32
	s_nop 0
	v_cndmask_b32_e32 v32, v32, v33, vcc
	v_rsq_f32_e32 v32, v32
	s_nop 0
	v_mul_f32_e32 v33, 0x45800000, v32
	v_cndmask_b32_e32 v38, v32, v33, vcc
	v_lshlrev_b64 v[32:33], 11, v[34:35]
	v_lshl_add_u64 v[40:41], s[38:39], 0, v[32:33]
	v_lshl_add_u64 v[36:37], s[92:93], 0, v[32:33]
	v_lshl_add_u64 v[32:33], v[40:41], 0, v[142:143]
	v_lshl_add_u64 v[36:37], v[36:37], 0, v[142:143]
	global_load_dwordx4 v[40:43], v[32:33], off
	global_load_dwordx4 v[44:47], v[36:37], off
	v_mul_f32_e32 v28, v28, v38
	v_mul_f32_e32 v29, v29, v38
	v_mul_f32_e32 v30, v30, v38
	v_mul_f32_e32 v31, v31, v38
	v_mul_f32_e32 v28, 0xbfb8aa3b, v28
	v_mul_f32_e32 v24, v24, v38
	v_mul_f32_e32 v29, 0xbfb8aa3b, v29
	v_mul_f32_e32 v25, v25, v38
	v_mul_f32_e32 v30, 0xbfb8aa3b, v30
	v_mul_f32_e32 v26, v26, v38
	v_mul_f32_e32 v31, 0xbfb8aa3b, v31
	v_mul_f32_e32 v27, v27, v38
	v_exp_f32_e32 v28, v28
	v_mul_f32_e32 v24, 0xbfb8aa3b, v24
	v_exp_f32_e32 v29, v29
	v_mul_f32_e32 v25, 0xbfb8aa3b, v25
	v_exp_f32_e32 v30, v30
	v_mul_f32_e32 v26, 0xbfb8aa3b, v26
	v_exp_f32_e32 v31, v31
	v_mul_f32_e32 v27, 0xbfb8aa3b, v27
	v_exp_f32_e32 v24, v24
	v_exp_f32_e32 v25, v25
	v_exp_f32_e32 v26, v26
	v_exp_f32_e32 v27, v27
	v_add_f32_e32 v28, 1.0, v28
	v_add_f32_e32 v29, 1.0, v29
	v_add_f32_e32 v30, 1.0, v30
	v_add_f32_e32 v31, 1.0, v31
	v_rcp_f32_e32 v28, v28
	v_add_f32_e32 v24, 1.0, v24
	v_rcp_f32_e32 v29, v29
	v_add_f32_e32 v25, 1.0, v25
	v_rcp_f32_e32 v30, v30
	v_add_f32_e32 v26, 1.0, v26
	v_rcp_f32_e32 v31, v31
	v_add_f32_e32 v27, 1.0, v27
	v_rcp_f32_e32 v24, v24
	v_rcp_f32_e32 v25, v25
	v_rcp_f32_e32 v26, v26
	v_rcp_f32_e32 v27, v27
	v_lshlrev_b64 v[34:35], 12, v[34:35]
	v_lshl_add_u64 v[34:35], s[88:89], 0, v[34:35]
	v_lshl_add_u64 v[34:35], v[34:35], 0, v[144:145]
	v_mul_f32_e32 v20, v20, v38
	v_mul_f32_e32 v21, v21, v38
	v_mul_f32_e32 v22, v22, v38
	v_mul_f32_e32 v23, v23, v38
	v_mul_f32_e32 v20, 0xbfb8aa3b, v20
	v_mul_f32_e32 v21, 0xbfb8aa3b, v21
	v_mul_f32_e32 v22, 0xbfb8aa3b, v22
	v_mul_f32_e32 v18, v18, v38
	v_mul_f32_e32 v23, 0xbfb8aa3b, v23
	v_mul_f32_e32 v19, v19, v38
	v_exp_f32_e32 v20, v20
	v_mul_f32_e32 v16, v16, v38
	v_exp_f32_e32 v21, v21
	v_mul_f32_e32 v17, v17, v38
	v_exp_f32_e32 v22, v22
	v_mul_f32_e32 v18, 0xbfb8aa3b, v18
	v_exp_f32_e32 v23, v23
	v_mul_f32_e32 v19, 0xbfb8aa3b, v19
	v_mul_f32_e32 v16, 0xbfb8aa3b, v16
	v_mul_f32_e32 v17, 0xbfb8aa3b, v17
	v_exp_f32_e32 v18, v18
	v_exp_f32_e32 v19, v19
	v_exp_f32_e32 v16, v16
	v_exp_f32_e32 v17, v17
	v_add_f32_e32 v20, 1.0, v20
	v_add_f32_e32 v21, 1.0, v21
	v_add_f32_e32 v22, 1.0, v22
	v_add_f32_e32 v23, 1.0, v23
	v_rcp_f32_e32 v20, v20
	v_rcp_f32_e32 v21, v21
	v_rcp_f32_e32 v22, v22
	v_add_f32_e32 v18, 1.0, v18
	v_rcp_f32_e32 v23, v23
	v_add_f32_e32 v19, 1.0, v19
	v_add_f32_e32 v16, 1.0, v16
	s_waitcnt vmcnt(1)
	v_lshlrev_b32_e32 v48, 16, v40
	v_and_b32_e32 v49, 0xffff0000, v40
	s_waitcnt vmcnt(0)
	v_lshlrev_b32_e32 v50, 16, v44
	v_and_b32_e32 v51, 0xffff0000, v44
	v_lshlrev_b32_e32 v40, 16, v41
	v_and_b32_e32 v41, 0xffff0000, v41
	v_lshlrev_b32_e32 v44, 16, v45
	v_and_b32_e32 v45, 0xffff0000, v45
	v_pk_fma_f32 v[28:29], v[28:29], v[50:51], v[48:49]
	v_lshlrev_b32_e32 v48, 16, v42
	v_and_b32_e32 v49, 0xffff0000, v42
	v_lshlrev_b32_e32 v50, 16, v46
	v_and_b32_e32 v51, 0xffff0000, v46
	v_pk_fma_f32 v[30:31], v[30:31], v[44:45], v[40:41]
	v_lshlrev_b32_e32 v40, 16, v43
	v_and_b32_e32 v41, 0xffff0000, v43
	v_lshlrev_b32_e32 v42, 16, v47
	v_and_b32_e32 v43, 0xffff0000, v47
	v_pk_fma_f32 v[24:25], v[24:25], v[50:51], v[48:49]
	v_pk_fma_f32 v[26:27], v[26:27], v[42:43], v[40:41]
	global_store_dwordx4 v[34:35], v[28:31], off
	global_store_dwordx4 v[34:35], v[24:27], off offset:16
	global_load_dwordx4 v[24:27], v[32:33], off offset:256
	s_nop 0
	global_load_dwordx4 v[28:31], v[36:37], off offset:256
	v_add_f32_e32 v17, 1.0, v17
	v_rcp_f32_e32 v18, v18
	v_rcp_f32_e32 v19, v19
	v_rcp_f32_e32 v16, v16
	v_rcp_f32_e32 v17, v17
	s_waitcnt vmcnt(1)
	v_lshlrev_b32_e32 v32, 16, v24
	v_and_b32_e32 v33, 0xffff0000, v24
	s_waitcnt vmcnt(0)
	v_lshlrev_b32_e32 v36, 16, v28
	v_and_b32_e32 v37, 0xffff0000, v28
	v_lshlrev_b32_e32 v24, 16, v25
	v_and_b32_e32 v25, 0xffff0000, v25
	v_lshlrev_b32_e32 v28, 16, v29
	v_and_b32_e32 v29, 0xffff0000, v29
	v_pk_fma_f32 v[20:21], v[20:21], v[36:37], v[32:33]
	v_lshlrev_b32_e32 v32, 16, v26
	v_and_b32_e32 v33, 0xffff0000, v26
	v_pk_fma_f32 v[22:23], v[22:23], v[28:29], v[24:25]
	v_lshlrev_b32_e32 v24, 16, v27
	v_and_b32_e32 v25, 0xffff0000, v27
	v_lshlrev_b32_e32 v26, 16, v31
	v_and_b32_e32 v27, 0xffff0000, v31
	v_lshlrev_b32_e32 v36, 16, v30
	v_and_b32_e32 v37, 0xffff0000, v30
	v_pk_fma_f32 v[18:19], v[18:19], v[26:27], v[24:25]
	v_pk_fma_f32 v[16:17], v[16:17], v[36:37], v[32:33]
	global_store_dwordx4 v[34:35], v[20:23], off offset:512
	global_store_dwordx4 v[34:35], v[16:19], off offset:528
	s_nop 1
	v_add_u32_e32 v18, 0xb0, v146
	v_ashrrev_i32_e32 v19, 31, v18
	v_lshl_add_u64 v[16:17], v[18:19], 2, s[90:91]
	v_add_co_u32_e32 v16, vcc, s11, v16
	s_nop 1
	v_addc_co_u32_e32 v17, vcc, 0, v17, vcc
	s_nop 0
	s_waitcnt vmcnt(56)
	v_fmamk_f32 v16, v249, 0x3a800000, v194
	v_cmp_gt_f32_e32 vcc, s19, v16
	v_mul_f32_e32 v17, 0x4b800000, v16
	s_nop 0
	v_cndmask_b32_e32 v16, v16, v17, vcc
	v_rsq_f32_e32 v16, v16
	s_nop 0
	v_mul_f32_e32 v17, 0x45800000, v16
	v_cndmask_b32_e32 v22, v16, v17, vcc
	v_lshlrev_b64 v[16:17], 11, v[18:19]
	v_lshl_add_u64 v[24:25], s[38:39], 0, v[16:17]
	v_lshl_add_u64 v[20:21], s[92:93], 0, v[16:17]
	v_lshl_add_u64 v[16:17], v[24:25], 0, v[142:143]
	v_lshl_add_u64 v[20:21], v[20:21], 0, v[142:143]
	global_load_dwordx4 v[24:27], v[16:17], off
	global_load_dwordx4 v[28:31], v[20:21], off
	v_mul_f32_e32 v12, v12, v22
	v_mul_f32_e32 v13, v13, v22
	v_mul_f32_e32 v14, v14, v22
	v_mul_f32_e32 v15, v15, v22
	v_mul_f32_e32 v12, 0xbfb8aa3b, v12
	v_mul_f32_e32 v8, v8, v22
	v_mul_f32_e32 v13, 0xbfb8aa3b, v13
	v_mul_f32_e32 v9, v9, v22
	v_mul_f32_e32 v14, 0xbfb8aa3b, v14
	v_mul_f32_e32 v10, v10, v22
	v_mul_f32_e32 v15, 0xbfb8aa3b, v15
	v_mul_f32_e32 v11, v11, v22
	v_exp_f32_e32 v12, v12
	v_mul_f32_e32 v8, 0xbfb8aa3b, v8
	v_exp_f32_e32 v13, v13
	v_mul_f32_e32 v9, 0xbfb8aa3b, v9
	v_exp_f32_e32 v14, v14
	v_mul_f32_e32 v10, 0xbfb8aa3b, v10
	v_exp_f32_e32 v15, v15
	v_mul_f32_e32 v11, 0xbfb8aa3b, v11
	v_exp_f32_e32 v8, v8
	v_exp_f32_e32 v9, v9
	v_exp_f32_e32 v10, v10
	v_exp_f32_e32 v11, v11
	v_add_f32_e32 v12, 1.0, v12
	v_add_f32_e32 v13, 1.0, v13
	v_add_f32_e32 v14, 1.0, v14
	v_add_f32_e32 v15, 1.0, v15
	v_rcp_f32_e32 v12, v12
	v_add_f32_e32 v8, 1.0, v8
	v_rcp_f32_e32 v13, v13
	v_add_f32_e32 v9, 1.0, v9
	v_rcp_f32_e32 v14, v14
	v_add_f32_e32 v10, 1.0, v10
	v_rcp_f32_e32 v15, v15
	v_add_f32_e32 v11, 1.0, v11
	v_rcp_f32_e32 v8, v8
	v_rcp_f32_e32 v9, v9
	v_rcp_f32_e32 v10, v10
	v_rcp_f32_e32 v11, v11
	v_lshlrev_b64 v[18:19], 12, v[18:19]
	v_lshl_add_u64 v[18:19], s[88:89], 0, v[18:19]
	v_lshl_add_u64 v[18:19], v[18:19], 0, v[144:145]
	v_mul_f32_e32 v4, v4, v22
	v_mul_f32_e32 v5, v5, v22
	v_mul_f32_e32 v6, v6, v22
	v_mul_f32_e32 v7, v7, v22
	v_mul_f32_e32 v4, 0xbfb8aa3b, v4
	v_mul_f32_e32 v0, v0, v22
	v_mul_f32_e32 v5, 0xbfb8aa3b, v5
	v_mul_f32_e32 v1, v1, v22
	v_mul_f32_e32 v6, 0xbfb8aa3b, v6
	v_mul_f32_e32 v2, v2, v22
	v_mul_f32_e32 v7, 0xbfb8aa3b, v7
	v_mul_f32_e32 v3, v3, v22
	v_exp_f32_e32 v4, v4
	v_mul_f32_e32 v0, 0xbfb8aa3b, v0
	v_exp_f32_e32 v5, v5
	v_mul_f32_e32 v1, 0xbfb8aa3b, v1
	v_exp_f32_e32 v6, v6
	v_mul_f32_e32 v2, 0xbfb8aa3b, v2
	v_exp_f32_e32 v7, v7
	v_mul_f32_e32 v3, 0xbfb8aa3b, v3
	v_exp_f32_e32 v0, v0
	v_exp_f32_e32 v1, v1
	v_exp_f32_e32 v2, v2
	v_exp_f32_e32 v3, v3
	v_add_f32_e32 v4, 1.0, v4
	v_add_f32_e32 v5, 1.0, v5
	v_add_f32_e32 v6, 1.0, v6
	v_add_f32_e32 v7, 1.0, v7
	v_rcp_f32_e32 v4, v4
	v_add_f32_e32 v0, 1.0, v0
	v_rcp_f32_e32 v5, v5
	v_add_f32_e32 v1, 1.0, v1
	v_rcp_f32_e32 v6, v6
	v_add_f32_e32 v2, 1.0, v2
	v_rcp_f32_e32 v7, v7
	s_waitcnt vmcnt(1)
	v_lshlrev_b32_e32 v32, 16, v24
	v_and_b32_e32 v33, 0xffff0000, v24
	s_waitcnt vmcnt(0)
	v_lshlrev_b32_e32 v34, 16, v28
	v_and_b32_e32 v35, 0xffff0000, v28
	v_lshlrev_b32_e32 v24, 16, v25
	v_and_b32_e32 v25, 0xffff0000, v25
	v_lshlrev_b32_e32 v28, 16, v29
	v_and_b32_e32 v29, 0xffff0000, v29
	v_pk_fma_f32 v[12:13], v[12:13], v[34:35], v[32:33]
	v_lshlrev_b32_e32 v32, 16, v26
	v_and_b32_e32 v33, 0xffff0000, v26
	v_lshlrev_b32_e32 v34, 16, v30
	v_and_b32_e32 v35, 0xffff0000, v30
	v_pk_fma_f32 v[14:15], v[14:15], v[28:29], v[24:25]
	v_lshlrev_b32_e32 v24, 16, v27
	v_and_b32_e32 v25, 0xffff0000, v27
	v_lshlrev_b32_e32 v26, 16, v31
	v_and_b32_e32 v27, 0xffff0000, v31
	v_pk_fma_f32 v[8:9], v[8:9], v[34:35], v[32:33]
	v_pk_fma_f32 v[10:11], v[10:11], v[26:27], v[24:25]
	global_store_dwordx4 v[18:19], v[12:15], off
	global_store_dwordx4 v[18:19], v[8:11], off offset:16
	global_load_dwordx4 v[8:11], v[16:17], off offset:256
	s_nop 0
	global_load_dwordx4 v[12:15], v[20:21], off offset:256
	v_add_f32_e32 v3, 1.0, v3
	v_rcp_f32_e32 v0, v0
	v_rcp_f32_e32 v1, v1
	v_rcp_f32_e32 v2, v2
	v_rcp_f32_e32 v3, v3
	s_andn2_b64 vcc, exec, s[42:43]
	s_waitcnt vmcnt(1)
	v_lshlrev_b32_e32 v16, 16, v8
	v_and_b32_e32 v17, 0xffff0000, v8
	s_waitcnt vmcnt(0)
	v_lshlrev_b32_e32 v20, 16, v12
	v_and_b32_e32 v21, 0xffff0000, v12
	v_lshlrev_b32_e32 v8, 16, v9
	v_and_b32_e32 v9, 0xffff0000, v9
	v_lshlrev_b32_e32 v12, 16, v13
	v_and_b32_e32 v13, 0xffff0000, v13
	v_pk_fma_f32 v[4:5], v[4:5], v[20:21], v[16:17]
	v_lshlrev_b32_e32 v16, 16, v10
	v_and_b32_e32 v17, 0xffff0000, v10
	v_lshlrev_b32_e32 v20, 16, v14
	v_and_b32_e32 v21, 0xffff0000, v14
	v_pk_fma_f32 v[6:7], v[6:7], v[12:13], v[8:9]
	v_lshlrev_b32_e32 v8, 16, v11
	v_and_b32_e32 v9, 0xffff0000, v11
	v_lshlrev_b32_e32 v10, 16, v15
	v_and_b32_e32 v11, 0xffff0000, v15
	v_pk_fma_f32 v[0:1], v[0:1], v[20:21], v[16:17]
	v_pk_fma_f32 v[2:3], v[2:3], v[10:11], v[8:9]
	global_store_dwordx4 v[18:19], v[4:7], off offset:512
	global_store_dwordx4 v[18:19], v[0:3], off offset:528
	s_cbranch_vccnz .LBB0_159
	s_andn2_b64 vcc, exec, s[0:1]
	s_cbranch_vccnz .LBB0_158
	s_barrier
	s_branch .LBB0_158
